# v11: fast first sync + norm param-load hoist + nb attention local blocks with batched bias lookups (validity folded into bias) + mixer A items rebalanced 1/2
# speedup vs baseline: 1.4094x; 1.0404x over previous
.LBB0_40:
	s_or_b64 exec, exec, s[0:1]
	s_waitcnt vmcnt(0) lgkmcnt(0)
	v_lshrrev_b32_e32 v1, 20, v0
	v_lshrrev_b32_e32 v0, 10, v0
	v_or_b32_e32 v0, v0, v1
	s_movk_i32 s0, 0x3ff
	v_and_or_b32 v0, v0, s0, v174
	s_barrier
	v_cmp_eq_u32_e64 s[0:1], 0, v0
	s_mov_b64 s[4:5], exec
	s_nop 0
	v_writelane_b32 v255, s0, 28
	s_nop 1
	v_writelane_b32 v255, s1, 29
	v_cmp_gt_u32_e64 s[0:1], 64, v174
	s_nop 1
	v_writelane_b32 v255, s0, 30
	s_nop 1
	v_writelane_b32 v255, s1, 31
	s_and_b64 s[0:1], s[4:5], s[0:1]
	s_mov_b64 exec, s[0:1]
	s_cbranch_execz .Lgs1_done
	s_mov_b64 exec, 1
	s_add_u32 s6, s56, 0x2480000
	s_addc_u32 s7, s57, 0
	s_and_b32 s8, s59, 7
	s_lshl_b32 s8, s8, 8
	v_mov_b32_e32 v0, s8
	v_mov_b32_e32 v1, 0
	v_mov_b32_e32 v2, 1
	v_readlane_b32 s10, v255, 16
	v_readlane_b32 s11, v255, 17
	global_load_dword v3, v0, s[6:7] offset:2048 sc1
	buffer_wbl2 sc1
	s_load_dwordx2 s[8:9], s[10:11], 0x58
	s_waitcnt vmcnt(0) lgkmcnt(0)
	global_atomic_add v2, v1, v2, s[8:9] offset:32 sc0
	s_waitcnt vmcnt(0)
	v_readfirstlane_b32 s10, v3
	v_readfirstlane_b32 s11, v2
	s_and_b32 s11, s11, 0xffff
	s_cmp_lg_u32 s11, 0xff
	s_cbranch_scc1 .Lgs1_poll
	v_mov_b32_e32 v3, 0x1000
	s_nop 1
	global_atomic_and v2, v1, v1, s[6:7] sc0
	global_atomic_and v2, v1, v1, s[6:7] offset:256 sc0
	global_atomic_and v2, v1, v1, s[6:7] offset:512 sc0
	global_atomic_and v2, v1, v1, s[6:7] offset:768 sc0
	global_atomic_and v2, v1, v1, s[6:7] offset:1024 sc0
	global_atomic_and v2, v1, v1, s[6:7] offset:1280 sc0
	global_atomic_and v2, v1, v1, s[6:7] offset:1536 sc0
	global_atomic_and v2, v1, v1, s[6:7] offset:1792 sc0
	global_atomic_and v2, v3, v1, s[6:7] sc0
	s_waitcnt vmcnt(0)
	v_mov_b32_e32 v2, 0xff00
	v_mov_b32_e32 v3, 1
	s_nop 1
	global_atomic_add v1, v2, s[8:9] offset:32
	global_atomic_add v1, v3, s[6:7] offset:2048
	global_atomic_add v1, v3, s[6:7] offset:2304
	global_atomic_add v1, v3, s[6:7] offset:2560
	global_atomic_add v1, v3, s[6:7] offset:2816
	global_atomic_add v1, v3, s[6:7] offset:3072
	global_atomic_add v1, v3, s[6:7] offset:3328
	global_atomic_add v1, v3, s[6:7] offset:3584
	global_atomic_add v1, v3, s[6:7] offset:3840

.Lgs1_done:
	s_mov_b64 exec, s[4:5]
	s_add_i32 s0, s3, 0x17f
	v_writelane_b32 v255, s0, 32
	s_ashr_i32 s33, s3, 31
	v_readlane_b32 s4, v255, 18
	v_readlane_b32 s5, v255, 19
	s_and_b64 s[0:1], s[4:5], exec
	s_cselect_b32 s17, 0x10000, s2
	s_abs_i32 s0, s3
	v_cvt_f32_u32_e32 v0, s0
	v_writelane_b32 v255, s0, 33
	s_sub_i32 s0, 0, s0
	s_ashr_i32 s29, s28, 31
	v_rcp_iflag_f32_e32 v0, v0
	s_lshl_b64 s[98:99], s[28:29], 12
	s_mov_b32 s31, 0
	s_lshl_b32 s21, s17, 3
	v_mul_f32_e32 v0, 0x4f7ffffe, v0
	v_cvt_u32_f32_e32 v0, v0
	v_mov_b32_e32 v1, 0
	s_movk_i32 s61, 0x1000
	s_movk_i32 s14, 0xfff
	v_readfirstlane_b32 s1, v0
	s_mul_i32 s0, s0, s1
	s_mul_hi_u32 s0, s1, s0
	s_add_i32 s0, s1, s0
	v_writelane_b32 v255, s0, 34
	s_add_i32 s0, 0, 0x11000
	v_writelane_b32 v255, s0, 35
	s_add_i32 s0, 0, 0xc800
	v_writelane_b32 v255, s0, 36
	s_mov_b32 s0, 0
	v_writelane_b32 v255, s0, 37
	v_writelane_b32 v255, s98, 38
	v_mbcnt_lo_u32_b32 v0, -1, 0
	v_mbcnt_hi_u32_b32 v176, -1, v0
	v_writelane_b32 v255, s99, 39
	v_writelane_b32 v255, s56, 40
	v_and_b32_e32 v0, 64, v176
	v_mov_b32_e32 v175, 0x358637bd
	v_writelane_b32 v255, s57, 41
	v_writelane_b32 v255, s59, 42
	v_writelane_b32 v255, s64, 43
	s_mov_b32 s15, 0x800000
	s_movk_i32 s16, 0xc00
	v_writelane_b32 v255, s65, 44
	v_writelane_b32 v255, s66, 45
	v_writelane_b32 v255, s67, 46
	v_writelane_b32 v255, s68, 47
	v_writelane_b32 v255, s69, 48
	v_writelane_b32 v255, s70, 49
	v_writelane_b32 v255, s71, 50
	v_writelane_b32 v255, s72, 51
	v_writelane_b32 v255, s73, 52
	v_writelane_b32 v255, s74, 53
	v_writelane_b32 v255, s75, 54
	v_writelane_b32 v255, s76, 55
	v_writelane_b32 v255, s77, 56
	v_writelane_b32 v255, s78, 57
	v_writelane_b32 v255, s79, 58
	v_writelane_b32 v255, s17, 59
	s_mov_b64 s[24:25], 0x1000
	s_movk_i32 s60, 0x55
	s_mov_b32 s96, 0x1fffe0
	s_mov_b64 s[26:27], 0x80
	s_movk_i32 s19, 0x1c00
	s_mov_b32 s40, 0x3fb8aa3b
	s_xor_b64 s[42:43], s[4:5], -1
	s_mov_b32 s18, 0x3e38aa3b
	s_mov_b32 s52, 0xff61b1e6
	s_movk_i32 s55, 0x101
	v_add_u32_e32 v177, 64, v0
	v_xor_b32_e32 v183, 1, v176
	v_xor_b32_e32 v182, 2, v176
	v_xor_b32_e32 v179, 4, v176
	v_xor_b32_e32 v254, 8, v176
	v_xor_b32_e32 v178, 32, v176
	v_mov_b32_e32 v184, 1
	v_mov_b32_e32 v185, 0xfff
	v_mov_b32_e32 v186, 0xf149f2ca
	v_mov_b32_e32 v187, 0x1000
	v_mov_b32_e32 v188, 0x1400
	v_mov_b32_e32 v189, 0xe00
	v_mov_b32_e32 v190, 0x800
	v_mov_b32_e32 v191, 0x1a00
	v_mov_b32_e32 v192, 0x1200
	v_mov_b32_e32 v193, 0x600
	v_mov_b32_e32 v194, 0x400
	v_mov_b64_e32 v[130:131], 0xc0
	v_mov_b64_e32 v[132:133], 0xbf
	s_mov_b32 s30, 0
	s_mov_b32 s34, s31
	v_writelane_b32 v255, s21, 60
	s_barrier
	s_branch .LBB0_54

.LBB0_61:
	s_or_b64 exec, exec, s[4:5]
	v_lshl_add_u64 v[6:7], v[2:3], 0, v[26:27]
	global_load_dwordx4 v[14:17], v[6:7], off
	global_load_dwordx4 v[10:13], v[6:7], off offset:1024
	global_load_dwordx4 v[2:5], v[6:7], off offset:3072
	s_nop 0
	global_load_dwordx4 v[6:9], v[6:7], off offset:2048
	v_ashrrev_i32_e32 v0, 12, v0
	v_mad_i32_i24 v0, v0, s16, s16
	v_cndmask_b32_e64 v36, v0, 0, vcc
	v_ashrrev_i32_e32 v37, 31, v36
	v_lshl_add_u64 v[38:39], v[36:37], 2, s[70:71]
	v_lshl_add_u64 v[36:37], v[38:39], 0, s[24:25]
	v_lshl_add_u64 v[46:47], v[36:37], 0, v[26:27]
	global_load_dwordx4 v[46:49], v[46:47], off
	s_nop 0
	global_load_dwordx4 v[50:53], v[18:19], off
	v_lshl_add_u64 v[38:39], v[38:39], 0, v[26:27]
	global_load_dwordx4 v[54:57], v[38:39], off
	v_lshl_add_u64 v[110:111], v[36:37], 0, v[28:29]
	v_lshl_add_u64 v[112:113], v[36:37], 0, v[30:31]
	v_lshl_add_u64 v[114:115], v[36:37], 0, v[32:33]
	global_load_dwordx4 v[74:77], v[18:19], off offset:1024
	global_load_dwordx4 v[86:89], v[110:111], off
	global_load_dwordx4 v[98:101], v[38:39], off offset:1024
	global_load_dwordx4 v[78:81], v[18:19], off offset:2048
	global_load_dwordx4 v[90:93], v[112:113], off
	global_load_dwordx4 v[102:105], v[38:39], off offset:2048
	global_load_dwordx4 v[82:85], v[18:19], off offset:3072
	global_load_dwordx4 v[94:97], v[114:115], off
	global_load_dwordx4 v[106:109], v[38:39], off offset:3072
	v_lshlrev_b64 v[34:35], 11, v[34:35]
	v_lshl_add_u64 v[34:35], v[20:21], 0, v[34:35]
	v_lshl_add_u64 v[22:23], v[22:23], 0, s[28:29]
	s_movk_i32 s0, 0x2fff
	v_lshl_add_u64 v[24:25], v[24:25], 0, s[98:99]
	s_waitcnt vmcnt(15)
	v_pk_mul_f32 v[58:59], v[16:17], v[16:17]
	v_pk_mul_f32 v[60:61], v[14:15], v[14:15]
	s_waitcnt vmcnt(14)
	v_pk_mul_f32 v[62:63], v[12:13], v[12:13]
	v_pk_mul_f32 v[64:65], v[10:11], v[10:11]
	v_pk_mov_b32 v[68:69], v[60:61], v[58:59] op_sel:[1,0]
	v_mov_b32_e32 v61, v59
	v_pk_mov_b32 v[58:59], v[64:65], v[62:63] op_sel:[1,0]
	v_mov_b32_e32 v65, v63
	s_waitcnt vmcnt(12)
	v_mul_f32_e32 v0, v7, v7
	v_mul_f32_e32 v66, v9, v9
	v_pk_add_f32 v[60:61], v[68:69], v[60:61]
	v_pk_add_f32 v[58:59], v[58:59], v[64:65]
	v_mul_f32_e32 v70, v4, v4
	v_mul_f32_e32 v71, v5, v5
	v_mul_f32_e32 v72, v2, v2
	v_mul_f32_e32 v73, v3, v3
	v_pk_fma_f32 v[62:63], v[6:7], v[6:7], v[0:1] op_sel_hi:[1,1,0]
	v_pk_fma_f32 v[66:67], v[8:9], v[8:9], v[66:67] op_sel_hi:[1,1,0]
	v_pk_add_f32 v[60:61], v[60:61], v[60:61] op_sel:[0,1] op_sel_hi:[1,0]
	v_pk_add_f32 v[58:59], v[58:59], v[58:59] op_sel:[0,1] op_sel_hi:[1,0]
	v_mov_b32_e32 v63, v70
	v_mov_b32_e32 v67, v71
	v_mov_b32_e32 v61, v72
	v_mov_b32_e32 v59, v73
	v_pk_add_f32 v[62:63], v[62:63], v[66:67]
	v_pk_add_f32 v[58:59], v[60:61], v[58:59]
	s_waitcnt vmcnt(11)
	v_pk_add_f32 v[48:49], v[48:49], 1.0 op_sel_hi:[1,0]
	v_pk_add_f32 v[58:59], v[58:59], v[62:63]
	v_pk_add_f32 v[46:47], v[46:47], 1.0 op_sel_hi:[1,0]
	v_add_f32_e32 v0, v58, v59
	ds_bpermute_b32 v58, v40, v0
	s_waitcnt lgkmcnt(0)
	v_add_f32_e32 v0, v0, v58
	ds_bpermute_b32 v58, v41, v0
	s_waitcnt lgkmcnt(0)
	v_add_f32_e32 v0, v0, v58
	ds_bpermute_b32 v58, v42, v0
	s_waitcnt lgkmcnt(0)
	v_add_f32_e32 v0, v0, v58
	ds_bpermute_b32 v58, v43, v0
	s_waitcnt lgkmcnt(0)
	v_add_f32_e32 v0, v0, v58
	ds_bpermute_b32 v58, v44, v0
	s_waitcnt lgkmcnt(0)
	v_add_f32_e32 v0, v0, v58
	ds_bpermute_b32 v58, v45, v0
	s_waitcnt lgkmcnt(0)
	v_add_f32_e32 v0, v0, v58
	v_fmamk_f32 v0, v0, 0x3a800000, v175
	v_mul_f32_e32 v58, 0x4b800000, v0
	v_cmp_gt_f32_e32 vcc, s15, v0
	s_nop 1
	v_cndmask_b32_e32 v0, v0, v58, vcc
	v_rsq_f32_e32 v0, v0
	s_nop 0
	v_mul_f32_e32 v58, 0x45800000, v0
	v_cndmask_b32_e32 v0, v0, v58, vcc
	v_pk_mul_f32 v[16:17], v[16:17], v[0:1] op_sel_hi:[1,0]
	v_pk_mul_f32 v[14:15], v[14:15], v[0:1] op_sel_hi:[1,0]
	s_waitcnt vmcnt(10)
	v_pk_mul_f32 v[16:17], v[52:53], v[16:17]
	v_pk_mul_f32 v[14:15], v[50:51], v[14:15]
	s_waitcnt vmcnt(9)
	v_pk_fma_f32 v[16:17], v[48:49], v[16:17], v[56:57]
	v_pk_fma_f32 v[14:15], v[46:47], v[14:15], v[54:55]
	v_cvt_pk_bf16_f32 v14, v14, v15
	v_cvt_pk_bf16_f32 v15, v16, v17
	global_store_dwordx2 v[34:35], v[14:15], off
	v_pk_mul_f32 v[12:13], v[12:13], v[0:1] op_sel_hi:[1,0]
	v_pk_mul_f32 v[10:11], v[10:11], v[0:1] op_sel_hi:[1,0]
	v_pk_mul_f32 v[8:9], v[8:9], v[0:1] op_sel_hi:[1,0]
	v_pk_mul_f32 v[6:7], v[6:7], v[0:1] op_sel_hi:[1,0]
	v_pk_mul_f32 v[4:5], v[4:5], v[0:1] op_sel_hi:[1,0]
	v_pk_mul_f32 v[2:3], v[2:3], v[0:1] op_sel_hi:[1,0]
	v_cmp_lt_i32_e32 vcc, s0, v22
	s_or_b64 s[8:9], vcc, s[8:9]
	s_waitcnt vmcnt(7)
	v_pk_mul_f32 v[10:11], v[74:75], v[10:11]
	v_pk_mul_f32 v[12:13], v[76:77], v[12:13]
	v_pk_add_f32 v[14:15], v[88:89], 1.0 op_sel_hi:[1,0]
	v_pk_add_f32 v[16:17], v[86:87], 1.0 op_sel_hi:[1,0]
	v_pk_fma_f32 v[12:13], v[14:15], v[12:13], v[100:101]
	v_pk_fma_f32 v[10:11], v[16:17], v[10:11], v[98:99]
	v_cvt_pk_bf16_f32 v10, v10, v11
	v_cvt_pk_bf16_f32 v11, v12, v13
	global_store_dwordx2 v[34:35], v[10:11], off offset:512
	s_waitcnt vmcnt(5)
	v_pk_mul_f32 v[6:7], v[78:79], v[6:7]
	v_pk_mul_f32 v[8:9], v[80:81], v[8:9]
	v_pk_add_f32 v[10:11], v[92:93], 1.0 op_sel_hi:[1,0]
	v_pk_add_f32 v[12:13], v[90:91], 1.0 op_sel_hi:[1,0]
	v_pk_fma_f32 v[8:9], v[10:11], v[8:9], v[104:105]
	v_pk_fma_f32 v[6:7], v[12:13], v[6:7], v[102:103]
	v_cvt_pk_bf16_f32 v6, v6, v7
	v_cvt_pk_bf16_f32 v7, v8, v9
	global_store_dwordx2 v[34:35], v[6:7], off offset:1024
	s_waitcnt vmcnt(3)
	v_pk_mul_f32 v[2:3], v[82:83], v[2:3]
	v_pk_mul_f32 v[4:5], v[84:85], v[4:5]
	v_pk_add_f32 v[6:7], v[96:97], 1.0 op_sel_hi:[1,0]
	v_pk_add_f32 v[8:9], v[94:95], 1.0 op_sel_hi:[1,0]
	v_pk_fma_f32 v[4:5], v[4:5], v[6:7], v[108:109]
	v_pk_fma_f32 v[2:3], v[2:3], v[8:9], v[106:107]
	s_nop 0
	v_cvt_pk_bf16_f32 v2, v2, v3
	v_cvt_pk_bf16_f32 v3, v4, v5
	global_store_dwordx2 v[34:35], v[2:3], off offset:1536
	s_andn2_b64 exec, exec, s[8:9]
	s_cbranch_execz .LBB0_66

.LBB0_162:
	s_andn2_b64 vcc, exec, s[6:7]
	s_cbranch_vccnz .LBB0_164
	s_cmpk_lt_i32 s58, 0x80
	s_cselect_b32 s0, 1, 2
.LBB0_164:
	s_add_u32 s6, s76, 0x3d00000
	s_addc_u32 s7, s77, 0
	s_add_u32 s8, s76, 0x9100000
	v_ashrrev_i32_e32 v101, 6, v100
	v_bfe_u32 v125, v100, 5, 1
	s_addc_u32 s9, s77, 0
	v_and_b32_e32 v124, 31, v100
	s_cmp_lt_i32 s0, 1
	v_lshlrev_b32_e32 v82, 4, v100
	v_lshlrev_b32_e32 v70, 5, v101
	v_lshlrev_b32_e32 v98, 4, v125
	s_cbranch_scc1 .LBB0_169
	v_cmp_lt_i32_e32 vcc, v183, v177
	s_lshl_b32 s1, s34, 18
	v_ashrrev_i32_e32 v30, 2, v100
	v_cndmask_b32_e32 v0, v176, v183, vcc
	v_cmp_lt_i32_e32 vcc, v182, v177
	v_lshlrev_b32_e32 v31, 2, v0
	s_add_u32 s10, s10, s1
	v_cndmask_b32_e32 v0, v176, v182, vcc
	v_lshlrev_b32_e32 v32, 2, v0
	v_and_b32_e32 v0, 0xffffffe0, v30
	s_addc_u32 s11, s11, 0
	v_ashrrev_i32_e32 v19, 31, v0
	v_or_b32_e32 v18, v0, v124
	v_lshlrev_b32_e32 v0, 5, v125
	v_lshl_add_u64 v[20:21], s[10:11], 0, v[0:1]
	v_and_b32_e32 v0, 32, v70
	s_lshl_b32 s30, s34, 9
	v_or_b32_e32 v3, v0, v124
	s_lshl_b64 s[12:13], s[30:31], 2
	v_and_b32_e32 v2, 48, v82
	v_mul_u32_u24_e32 v3, 0x110, v3
	s_add_u32 s4, s4, s12
	v_add3_u32 v33, 0, v3, v98
	v_lshl_or_b32 v4, v125, 2, v0
	v_mul_u32_u24_e32 v0, 0x110, v2
	v_lshlrev_b32_e32 v3, 1, v30
	s_addc_u32 s5, s5, s13
	s_mul_i32 s1, s58, 1
	s_add_i32 s2, s58, 0xffffff80
	s_mul_i32 s2, s2, 2
	s_addk_i32 s2, 0x80
	s_cmpk_lt_i32 s58, 0x80
	s_cselect_b32 s1, s1, s2
	s_mov_b32 s2, 0
	v_add3_u32 v34, 0, v0, v3
	v_lshlrev_b32_e32 v0, 1, v2
	v_lshlrev_b32_e32 v22, 1, v4
	s_branch .LBB0_167

.LBB0_218:
	v_cmp_lt_i32_e32 vcc, s20, v114
	s_or_b64 s[0:1], s[42:43], vcc
	s_and_saveexec_b64 s[82:83], s[0:1]
	s_cbranch_execz .LBB0_217
	v_lshlrev_b32_e32 v96, 1, v84
	s_and_saveexec_b64 s[0:1], vcc
	s_xor_b64 s[84:85], exec, s[0:1]
	s_cbranch_execz .LBB0_225
	v_lshrrev_b32_e32 v0, 5, v110
	v_and_b32_e32 v0, 0x7fffff0, v0
	v_bfe_u32 v120, v114, 7, 2
	v_readlane_b32 s0, v255, 37
	v_bfe_u32 v115, v114, 1, 6
	v_mov_b64_e32 v[2:3], s[6:7]
	v_add3_u32 v0, s0, v0, v120
	v_lshlrev_b64 v[104:105], 16, v[0:1]
	v_add_u32_e32 v0, 0xfffffc00, v114
	v_lshrrev_b32_e32 v121, 9, v0
	v_lshlrev_b32_e32 v0, 5, v114
	v_and_or_b32 v116, v0, 32, v124
	v_lshl_add_u32 v122, v121, 12, v187
	v_lshlrev_b32_e32 v0, 6, v115
	v_or3_b32 v0, v122, v0, v116
	v_mov_b64_e32 v[94:95], v[0:1]
	v_mad_u64_u32 v[102:103], s[0:1], v0, s19, v[2:3]
	v_lshlrev_b32_e32 v0, 7, v120
	v_lshl_add_u64 v[2:3], v[102:103], 0, v[0:1]
	v_mov_b32_e32 v97, v1
	v_lshl_add_u64 v[2:3], v[2:3], 0, v[96:97]
	s_mov_b64 s[0:1], 0x1400
	v_lshl_add_u64 v[4:5], v[2:3], 0, s[0:1]
	v_add_co_u32_e32 v2, vcc, s61, v2
	v_mov_b32_e32 v123, 0
	s_nop 0
	v_addc_co_u32_e32 v3, vcc, 0, v3, vcc
	global_load_dwordx4 v[50:53], v[4:5], off offset:32
	global_load_dwordx4 v[54:57], v[4:5], off offset:64
	global_load_dwordx4 v[58:61], v[2:3], off offset:1024
	global_load_dwordx4 v[62:65], v[4:5], off offset:96
	v_cmp_lt_i32_e32 vcc, v178, v177
	s_mov_b32 s0, 16
	v_lshlrev_b32_e32 v100, 6, v120
	v_cndmask_b32_e32 v0, v176, v178, vcc
	v_mov_b32_e32 v101, v1
	v_lshlrev_b32_e32 v117, 2, v0
	v_mov_b32_e32 v118, 0xf149f2ca
	v_mov_b64_e32 v[106:107], v[92:93]
	v_mov_b64_e32 v[108:109], v[90:91]
	v_mov_b32_e32 v18, 0
	v_mov_b32_e32 v19, v123
	v_mov_b32_e32 v20, v123
	v_mov_b32_e32 v21, v123
	v_mov_b32_e32 v22, v123
	v_mov_b32_e32 v23, v123
	v_mov_b32_e32 v24, v123
	v_mov_b32_e32 v25, v123
	v_mov_b32_e32 v26, v123
	v_mov_b32_e32 v27, v123
	v_mov_b32_e32 v28, v123
	v_mov_b32_e32 v29, v123
	v_mov_b32_e32 v30, v123
	v_mov_b32_e32 v31, v123
	v_mov_b32_e32 v32, v123
	v_mov_b32_e32 v33, v123
	v_mov_b32_e32 v2, 0
	v_mov_b32_e32 v3, v123
	v_mov_b32_e32 v4, v123
	v_mov_b32_e32 v5, v123
	v_mov_b32_e32 v6, v123
	v_mov_b32_e32 v7, v123
	v_mov_b32_e32 v8, v123
	v_mov_b32_e32 v9, v123
	v_mov_b32_e32 v10, v123
	v_mov_b32_e32 v11, v123
	v_mov_b32_e32 v12, v123
	v_mov_b32_e32 v13, v123
	v_mov_b32_e32 v14, v123
	v_mov_b32_e32 v15, v123
	v_mov_b32_e32 v16, v123
	v_mov_b32_e32 v17, v123
	v_mov_b32_e32 v244, 0x1ffc
	ds_write_b32 v244, v186
	v_lshrrev_b32_e32 v244, 6, v174
	v_mul_u32_u24_e32 v244, 0x2600, v244
	v_add_u32_e32 v244, 0x2000, v244
	v_lshrrev_b32_e32 v245, 3, v176
	v_mul_u32_u24_e32 v245, 0x90, v245
	v_and_b32_e32 v195, 7, v176
	v_lshl_add_u32 v245, v195, 4, v245
	v_add_u32_e32 v245, v245, v244
	v_lshrrev_b32_e32 v246, 2, v176
	v_mul_u32_u24_e32 v246, 0x50, v246
	v_and_b32_e32 v195, 3, v176
	v_lshl_add_u32 v246, v195, 4, v246
	v_add_u32_e32 v246, v246, v244
	v_add_u32_e32 v246, 0x1200, v246
	v_mul_u32_u24_e32 v247, 0x90, v124
	v_lshl_add_u32 v247, v125, 4, v247
	v_add_u32_e32 v247, v247, v244
	v_mul_u32_u24_e32 v252, 0x50, v124
	v_lshl_add_u32 v252, v125, 3, v252
	v_add_u32_e32 v252, v252, v244
	v_add_u32_e32 v252, 0x1200, v252
	v_add_u32_e32 v253, 0xa00, v252
	v_lshlrev_b32_e32 v244, 4, v176
	v_add_u32_e32 v196, v104, v244
	v_add_u32_e32 v196, 0xe400000, v196
	v_add_u32_e32 v197, 0x400, v196
	v_add_u32_e32 v198, 0x800, v196
	v_add_u32_e32 v199, 0xc00, v196
	v_lshrrev_b32_e32 v244, 2, v176
	v_lshlrev_b32_e32 v195, 4, v195
	v_lshl_add_u32 v200, v244, 10, v195
	v_add_u32_e32 v200, v200, v104
	v_add_u32_e32 v200, 0xe600000, v200
	v_add_u32_e32 v201, 0x4000, v200
	v_add_u32_e32 v202, 0x8000, v200
	v_add_u32_e32 v203, 0xc000, v200
	v_sub_u32_e64 v208, v115, 4 clamp
	v_min_u32_e32 v208, 56, v208
	v_lshlrev_b32_e32 v208, 6, v208
	v_lshl_add_u32 v204, v121, 12, v208
	v_add_u32_e32 v204, 0x1000, v204
	v_lshrrev_b32_e32 v205, 3, v176
	v_add_u32_e32 v204, v204, v205
	v_mul_lo_u32 v204, v204, s19
	v_and_b32_e32 v205, 7, v176
	v_lshlrev_b32_e32 v205, 4, v205
	v_lshl_add_u32 v205, v120, 7, v205
	v_add_u32_e32 v204, v204, v205
	v_add_u32_e32 v204, 0x3d01600, v204
	v_add_u32_e32 v205, 0xe000, v204
	v_add_u32_e32 v206, 0x1c000, v204
	v_add_u32_e32 v207, 0x2a000, v204
	v_lshl_add_u32 v209, v121, 2, v120
	v_lshl_add_u32 v209, v209, 6, v244
	v_lshlrev_b32_e32 v209, 13, v209
	v_lshl_add_u32 v208, v208, 1, v209
	v_add_u32_e32 v208, v208, v195
	v_add_u32_e32 v208, 0xde00000, v208
	v_add_u32_e32 v209, 0x20000, v208
	v_add_u32_e32 v210, 0x40000, v208
	v_add_u32_e32 v211, 0x60000, v208
	global_load_dwordx4 v[212:215], v196, s[56:57]
	global_load_dwordx4 v[216:219], v197, s[56:57]
	global_load_dwordx4 v[220:223], v198, s[56:57]
	global_load_dwordx4 v[224:227], v199, s[56:57]
	global_load_dwordx4 v[228:231], v200, s[56:57]
	global_load_dwordx4 v[232:235], v201, s[56:57]
	global_load_dwordx4 v[236:239], v202, s[56:57]
	global_load_dwordx4 v[240:243], v203, s[56:57]
	v_add_u32_e32 v196, 0x1000, v196
	v_add_u32_e32 v197, 0x1000, v197
	v_add_u32_e32 v198, 0x1000, v198
	v_add_u32_e32 v199, 0x1000, v199
	v_add_u32_e32 v200, 64, v200
	v_add_u32_e32 v201, 64, v201
	v_add_u32_e32 v202, 64, v202
	v_add_u32_e32 v203, 64, v203
	s_waitcnt vmcnt(0)
	ds_write_b128 v245, v[212:215]
	ds_write_b128 v245, v[216:219] offset:1152
	ds_write_b128 v245, v[220:223] offset:2304
	ds_write_b128 v245, v[224:227] offset:3456
	ds_write_b128 v246, v[228:231]
	ds_write_b128 v246, v[232:235] offset:1280
	ds_write_b128 v246, v[236:239] offset:2560
	ds_write_b128 v246, v[240:243] offset:3840
	s_waitcnt lgkmcnt(0)
	global_load_dwordx4 v[212:215], v196, s[56:57]
	global_load_dwordx4 v[216:219], v197, s[56:57]
	global_load_dwordx4 v[220:223], v198, s[56:57]
	global_load_dwordx4 v[224:227], v199, s[56:57]
	global_load_dwordx4 v[228:231], v200, s[56:57]
	global_load_dwordx4 v[232:235], v201, s[56:57]
	global_load_dwordx4 v[236:239], v202, s[56:57]
	global_load_dwordx4 v[240:243], v203, s[56:57]
	v_add_u32_e32 v196, 0x1000, v196
	v_add_u32_e32 v197, 0x1000, v197
	v_add_u32_e32 v198, 0x1000, v198
	v_add_u32_e32 v199, 0x1000, v199
	v_add_u32_e32 v200, 64, v200
	v_add_u32_e32 v201, 64, v201
	v_add_u32_e32 v202, 64, v202
	v_add_u32_e32 v203, 64, v203

.LBB0_223:
	s_lshr_b32 s2, s1, 1
	v_add_u32_e32 v0, s2, v105
	s_and_b32 s2, s0, 32
	v_sub_u32_e32 v0, v0, v115
	s_movk_i32 s4, 0x7c
	v_mad_u64_u32 v[108:109], s[4:5], v0, s4, v[104:105]
	v_lshlrev_b32_e32 v0, 1, v100
	v_or_b32_e32 v109, s2, v82
	v_mov_b32_e32 v122, v123
	v_sub_u32_e32 v36, v109, v119
	v_sub_u32_e32 v37, v109, v116
	v_add_u32_e32 v37, 15, v37
	v_lshl_add_u32 v108, v37, 2, v108
	v_mov_b32_e32 v37, 0x1c98
	v_cmp_gt_u32_e32 vcc, 16, v36
	v_mov_b32_e32 v162, v108
	s_nop 0
	v_cndmask_b32_e32 v162, v37, v162, vcc
	ds_read_b32 v162, v162 offset:868
	v_add_u32_e32 v35, 1, v36
	v_cmp_gt_u32_e32 vcc, 16, v35
	v_add_u32_e32 v163, 4, v108
	s_nop 0
	v_cndmask_b32_e32 v163, v37, v163, vcc
	ds_read_b32 v163, v163 offset:868
	v_add_u32_e32 v35, 2, v36
	v_cmp_gt_u32_e32 vcc, 16, v35
	v_add_u32_e32 v164, 8, v108
	s_nop 0
	v_cndmask_b32_e32 v164, v37, v164, vcc
	ds_read_b32 v164, v164 offset:868
	v_add_u32_e32 v35, 3, v36
	v_cmp_gt_u32_e32 vcc, 16, v35
	v_add_u32_e32 v165, 12, v108
	s_nop 0
	v_cndmask_b32_e32 v165, v37, v165, vcc
	ds_read_b32 v165, v165 offset:868
	v_add_u32_e32 v35, 8, v36
	v_cmp_gt_u32_e32 vcc, 16, v35
	v_add_u32_e32 v166, 32, v108
	s_nop 0
	v_cndmask_b32_e32 v166, v37, v166, vcc
	ds_read_b32 v166, v166 offset:868
	v_add_u32_e32 v35, 9, v36
	v_cmp_gt_u32_e32 vcc, 16, v35
	v_add_u32_e32 v167, 36, v108
	s_nop 0
	v_cndmask_b32_e32 v167, v37, v167, vcc
	ds_read_b32 v167, v167 offset:868
	v_add_u32_e32 v35, 10, v36
	v_cmp_gt_u32_e32 vcc, 16, v35
	v_add_u32_e32 v168, 40, v108
	s_nop 0
	v_cndmask_b32_e32 v168, v37, v168, vcc
	ds_read_b32 v168, v168 offset:868
	v_add_u32_e32 v35, 11, v36
	v_cmp_gt_u32_e32 vcc, 16, v35
	v_add_u32_e32 v169, 44, v108
	s_nop 0
	v_cndmask_b32_e32 v169, v37, v169, vcc
	ds_read_b32 v169, v169 offset:868
	v_add_u32_e32 v35, 16, v36
	v_cmp_gt_u32_e32 vcc, 16, v35
	v_add_u32_e32 v170, 64, v108
	s_nop 0
	v_cndmask_b32_e32 v170, v37, v170, vcc
	ds_read_b32 v170, v170 offset:868
	v_add_u32_e32 v35, 17, v36
	v_cmp_gt_u32_e32 vcc, 16, v35
	v_add_u32_e32 v171, 68, v108
	s_nop 0
	v_cndmask_b32_e32 v171, v37, v171, vcc
	ds_read_b32 v171, v171 offset:868
	v_add_u32_e32 v35, 18, v36
	v_cmp_gt_u32_e32 vcc, 16, v35
	v_add_u32_e32 v172, 72, v108
	s_nop 0
	v_cndmask_b32_e32 v172, v37, v172, vcc
	ds_read_b32 v172, v172 offset:868
	v_add_u32_e32 v35, 19, v36
	v_cmp_gt_u32_e32 vcc, 16, v35
	v_add_u32_e32 v173, 76, v108
	s_nop 0
	v_cndmask_b32_e32 v173, v37, v173, vcc
	ds_read_b32 v173, v173 offset:868
	v_add_u32_e32 v35, 24, v36
	v_cmp_gt_u32_e32 vcc, 16, v35
	v_add_u32_e32 v195, 96, v108
	s_nop 0
	v_cndmask_b32_e32 v195, v37, v195, vcc
	ds_read_b32 v195, v195 offset:868
	v_add_u32_e32 v35, 25, v36
	v_cmp_gt_u32_e32 vcc, 16, v35
	v_add_u32_e32 v244, 100, v108
	s_nop 0
	v_cndmask_b32_e32 v244, v37, v244, vcc
	ds_read_b32 v244, v244 offset:868
	v_add_u32_e32 v35, 26, v36
	v_cmp_gt_u32_e32 vcc, 16, v35
	v_add_u32_e32 v97, 104, v108
	s_nop 0
	v_cndmask_b32_e32 v97, v37, v97, vcc
	ds_read_b32 v97, v97 offset:868
	v_add_u32_e32 v35, 27, v36
	v_cmp_gt_u32_e32 vcc, 16, v35
	v_add_u32_e32 v123, 108, v108
	s_nop 0
	v_cndmask_b32_e32 v123, v37, v123, vcc
	ds_read_b32 v123, v123 offset:868
	s_add_i32 s1, s1, 1
	s_add_i32 s0, s0, 32
	ds_read_b128 v[248:251], v247
	ds_read_b128 v[126:129], v247 offset:32
	ds_read_b128 v[134:137], v247 offset:64
	ds_read_b128 v[138:141], v247 offset:96
	ds_read2_b64 v[78:81], v252 offset1:2
	ds_read2_b64 v[74:77], v253 offset1:2
	ds_read2_b64 v[70:73], v252 offset0:4 offset1:6
	ds_read2_b64 v[66:69], v253 offset0:4 offset1:6
	s_waitcnt vmcnt(0)
	ds_write_b128 v245, v[212:215]
	ds_write_b128 v245, v[216:219] offset:1152
	ds_write_b128 v245, v[220:223] offset:2304
	ds_write_b128 v245, v[224:227] offset:3456
	ds_write_b128 v246, v[228:231]
	ds_write_b128 v246, v[232:235] offset:1280
	ds_write_b128 v246, v[236:239] offset:2560
	ds_write_b128 v246, v[240:243] offset:3840
	s_waitcnt lgkmcnt(8)
	v_mfma_f32_32x32x16_bf16 v[34:49], v[248:251], v[58:61], 0
	v_mfma_f32_32x32x16_bf16 v[34:49], v[126:129], v[50:53], v[34:49]
	v_mfma_f32_32x32x16_bf16 v[34:49], v[134:137], v[54:57], v[34:49]
	v_mfma_f32_32x32x16_bf16 v[34:49], v[138:141], v[62:65], v[34:49]
	s_waitcnt lgkmcnt(0)
	s_cmp_ge_u32 s1, 31
	s_cbranch_scc1 .Lnb_l_skip
	global_load_dwordx4 v[212:215], v204, s[56:57]
	global_load_dwordx4 v[216:219], v205, s[56:57]
	global_load_dwordx4 v[220:223], v206, s[56:57]
	global_load_dwordx4 v[224:227], v207, s[56:57]
	global_load_dwordx4 v[228:231], v208, s[56:57]
	global_load_dwordx4 v[232:235], v209, s[56:57]
	global_load_dwordx4 v[236:239], v210, s[56:57]
	global_load_dwordx4 v[240:243], v211, s[56:57]
	v_add_u32_e32 v204, 0x38000, v204
	v_add_u32_e32 v205, 0x38000, v205
	v_add_u32_e32 v206, 0x38000, v206
	v_add_u32_e32 v207, 0x38000, v207
	v_add_u32_e32 v208, 64, v208
	v_add_u32_e32 v209, 64, v209
	v_add_u32_e32 v210, 64, v210
	v_add_u32_e32 v211, 64, v211
	s_branch .Lnb_l_cont

.Lnb_l_cont:
	v_fma_f32 v34, v34, s18, v162
	v_fma_f32 v35, v35, s18, v163
	v_fma_f32 v36, v36, s18, v164
	v_fma_f32 v37, v37, s18, v165
	v_fma_f32 v38, v38, s18, v166
	v_fma_f32 v39, v39, s18, v167
	v_fma_f32 v40, v40, s18, v168
	v_fma_f32 v41, v41, s18, v169
	v_fma_f32 v42, v42, s18, v170
	v_fma_f32 v43, v43, s18, v171
	v_fma_f32 v44, v44, s18, v172
	v_fma_f32 v45, v45, s18, v173
	v_fma_f32 v46, v46, s18, v195
	v_fma_f32 v47, v47, s18, v244
	v_fma_f32 v48, v48, s18, v97
	v_fma_f32 v49, v49, s18, v123
	v_max3_f32 v97, v34, s52, v35
	v_max3_f32 v97, v97, v36, v37
	v_max3_f32 v97, v97, v38, v39
	v_max3_f32 v97, v97, v40, v41
	v_max3_f32 v97, v97, v42, v43
	v_max3_f32 v97, v97, v44, v45
	v_max3_f32 v97, v97, v46, v47
	v_max3_f32 v97, v97, v48, v49
	s_cmp_eq_u32 s1, 16
	ds_bpermute_b32 v108, v117, v97
	s_waitcnt lgkmcnt(0)
	v_max3_f32 v97, v118, v97, v108
	v_sub_f32_e32 v34, v34, v97
	v_exp_f32_e32 v109, v34
	v_sub_f32_e32 v35, v35, v97
	v_exp_f32_e32 v35, v35
	v_sub_f32_e32 v36, v36, v97
	v_exp_f32_e32 v36, v36
	v_sub_f32_e32 v37, v37, v97
	v_exp_f32_e32 v37, v37
	v_sub_f32_e32 v38, v38, v97
	v_add_f32_e32 v34, 0, v109
	v_exp_f32_e32 v38, v38
	v_sub_f32_e32 v39, v39, v97
	v_add_f32_e32 v34, v35, v34
	v_exp_f32_e32 v39, v39
	v_sub_f32_e32 v40, v40, v97
	v_add_f32_e32 v34, v36, v34
	v_exp_f32_e32 v40, v40
	v_sub_f32_e32 v41, v41, v97
	v_add_f32_e32 v34, v37, v34
	v_exp_f32_e32 v41, v41
	v_sub_f32_e32 v42, v42, v97
	v_add_f32_e32 v34, v38, v34
	v_exp_f32_e32 v42, v42
	v_sub_f32_e32 v43, v43, v97
	v_add_f32_e32 v34, v39, v34
	v_exp_f32_e32 v43, v43
	v_sub_f32_e32 v44, v44, v97
	v_add_f32_e32 v34, v40, v34
	v_exp_f32_e32 v44, v44
	v_sub_f32_e32 v45, v45, v97
	v_add_f32_e32 v34, v41, v34
	v_exp_f32_e32 v45, v45
	v_sub_f32_e32 v46, v46, v97
	v_add_f32_e32 v34, v42, v34
	v_exp_f32_e32 v46, v46
	v_sub_f32_e32 v47, v47, v97
	v_add_f32_e32 v34, v43, v34
	v_exp_f32_e32 v47, v47
	v_sub_f32_e32 v48, v48, v97
	v_add_f32_e32 v34, v44, v34
	v_exp_f32_e32 v48, v48
	v_sub_f32_e32 v49, v49, v97
	v_add_f32_e32 v34, v45, v34
	v_exp_f32_e32 v49, v49
	v_add_f32_e32 v34, v46, v34
	v_add_f32_e32 v34, v47, v34
	v_add_f32_e32 v34, v48, v34
	v_sub_f32_e32 v108, v118, v97
	v_add_f32_e32 v118, v49, v34
	v_exp_f32_e32 v34, v108
	ds_bpermute_b32 v108, v117, v118
	v_pk_mul_f32 v[32:33], v[32:33], v[34:35] op_sel_hi:[1,0]
	v_pk_mul_f32 v[30:31], v[30:31], v[34:35] op_sel_hi:[1,0]
	s_waitcnt lgkmcnt(0)
	v_add_f32_e32 v123, v118, v108
	v_fmac_f32_e32 v123, v122, v34
	v_pk_mul_f32 v[28:29], v[28:29], v[34:35] op_sel_hi:[1,0]
	v_pk_mul_f32 v[26:27], v[26:27], v[34:35] op_sel_hi:[1,0]
	v_pk_mul_f32 v[24:25], v[24:25], v[34:35] op_sel_hi:[1,0]
	v_pk_mul_f32 v[22:23], v[22:23], v[34:35] op_sel_hi:[1,0]
	v_pk_mul_f32 v[20:21], v[20:21], v[34:35] op_sel_hi:[1,0]
	v_pk_mul_f32 v[18:19], v[18:19], v[34:35] op_sel_hi:[1,0]
	v_pk_mul_f32 v[16:17], v[16:17], v[34:35] op_sel_hi:[1,0]
	v_pk_mul_f32 v[14:15], v[14:15], v[34:35] op_sel_hi:[1,0]
	v_pk_mul_f32 v[12:13], v[12:13], v[34:35] op_sel_hi:[1,0]
	v_pk_mul_f32 v[10:11], v[10:11], v[34:35] op_sel_hi:[1,0]
	v_pk_mul_f32 v[8:9], v[8:9], v[34:35] op_sel_hi:[1,0]
	v_pk_mul_f32 v[6:7], v[6:7], v[34:35] op_sel_hi:[1,0]
	v_pk_mul_f32 v[4:5], v[4:5], v[34:35] op_sel_hi:[1,0]
	v_pk_mul_f32 v[2:3], v[2:3], v[34:35] op_sel_hi:[1,0]
	v_cvt_pk_bf16_f32 v34, v109, v35
	v_cvt_pk_bf16_f32 v35, v36, v37
	v_cvt_pk_bf16_f32 v36, v38, v39
	v_cvt_pk_bf16_f32 v37, v40, v41
	v_mov_b32_e32 v118, v97
	s_nop 0
	v_mfma_f32_32x32x16_bf16 v[18:33], v[78:81], v[34:37], v[18:33]
	s_nop 0
	v_mfma_f32_32x32x16_bf16 v[2:17], v[74:77], v[34:37], v[2:17]
	v_cvt_pk_bf16_f32 v34, v42, v43
	v_cvt_pk_bf16_f32 v35, v44, v45
	v_cvt_pk_bf16_f32 v36, v46, v47
	v_cvt_pk_bf16_f32 v37, v48, v49
	s_nop 1
	v_mfma_f32_32x32x16_bf16 v[18:33], v[70:73], v[34:37], v[18:33]
	s_nop 0
	v_mfma_f32_32x32x16_bf16 v[2:17], v[66:69], v[34:37], v[2:17]
	s_cbranch_scc0 .LBB0_223
	v_lshl_add_u64 v[34:35], v[102:103], 0, v[0:1]
	s_mov_b64 s[0:1], 0x1a00
	v_lshl_add_u64 v[36:37], v[34:35], 0, s[0:1]
